# weight conversions not needed by the first projection GEMM moved from phase 0 into phase 1; half of the workgroups convert before their GEMM tiles, half after, so conversion overlaps the GEMM across w
# speedup vs baseline: 1.0101x; 1.0057x over previous
; #define LAS __attribute__((address_space(3)))
; __device__ __forceinline__ void run_phase(const Params& p, int ph, LAS unsigned char* lds) {
;     unsigned char* ws = p.ws;
;     if (ph == 0) { phase_convert(p, lds); return; }
;     const int l = (ph - 1) / PH_PER_LAYER, k = (ph - 1) % PH_PER_LAYER;
;     bf16_t* PROJ = (bf16_t*)(ws + WS_PROJ); bf16_t* YCAT = (bf16_t*)(ws + WS_YCAT);
; __global__ void __launch_bounds__(NTHREADS, 2) mega(Params p) {
;     extern __shared__ __attribute__((aligned(16))) unsigned char lds_raw[];
;     LAS unsigned char* lds = (LAS unsigned char*)lds_raw;
;     cg::grid_group grid = cg::this_grid();
;     for (int ph = p.ph_lo; ph < p.ph_hi; ++ph) {
;         if (ph > p.ph_lo) { if (p.ph_hi > 4096) grid.sync();   else grid_barrier((unsigned*)p.ws, (unsigned)(ph - p.ph_lo)); }
.LBB0_1:
	s_mov_b32 s58, s2
	s_add_u32 s2, s0, 0xb0
	s_addc_u32 s3, s1, 0
	s_cmpk_lt_i32 s57, 0x1001
	v_writelane_b32 v252, s2, 0
	s_load_dword s59, s[0:1], 0xb0
	s_load_dwordx2 s[86:87], s[0:1], 0xa0
	v_writelane_b32 v252, s3, 1
	s_cselect_b64 s[2:3], -1, 0
	v_writelane_b32 v252, s2, 2
	s_mov_b32 s91, 0
	s_load_dwordx8 s[76:83], s[0:1], 0x80
	v_writelane_b32 v252, s3, 3
	s_and_b32 s2, s58, 7
	s_xor_b32 s3, s2, 7
	s_waitcnt lgkmcnt(0)
	s_add_i32 s3, s59, s3
	s_lshr_b32 s61, s3, 3
	s_min_u32 s3, s59, 8
	s_lshl_b32 s2, s2, 7
	s_add_u32 s72, s86, s2
	s_addc_u32 s73, s87, 0
	s_add_u32 s94, s86, 0x20601000
	s_addc_u32 s95, s87, 0
	s_add_u32 s24, s86, 0x2e601000
	s_addc_u32 s25, s87, 0
	s_add_u32 s2, s86, 0x28601000
	v_writelane_b32 v252, s3, 4
	s_addc_u32 s3, s87, 0
	s_add_u32 s66, s86, 0x1a601000
	s_addc_u32 s67, s87, 0
	v_writelane_b32 v252, s2, 5
	s_add_u32 s28, s86, 0x33741000
	s_addc_u32 s29, s87, 0
	v_writelane_b32 v252, s3, 6
	s_lshl_b32 s30, s59, 3
	s_lshl_b32 s2, s58, 3
	s_add_u32 s64, s86, 0x12601000
	s_addc_u32 s33, s87, 0
	s_add_u32 s8, s86, 0x33721000
	s_addc_u32 s9, s87, 0
	s_cmpk_lt_i32 s58, 0x200
	v_writelane_b32 v252, s2, 7
	s_cselect_b64 s[2:3], -1, 0
	v_writelane_b32 v252, s2, 8
	s_ashr_i32 s68, s58, 31
	s_ashr_i32 s62, s59, 31
	v_writelane_b32 v252, s3, 9
	s_lshr_b32 s2, s68, 29
	s_add_i32 s2, s58, s2
	s_ashr_i32 s4, s2, 3
	s_and_b32 s2, s2, -8
	s_sub_i32 s5, s58, s2
	s_lshl_b32 s6, s5, 6
	s_add_u32 s10, s86, 0x33701000
	s_addc_u32 s11, s87, 0
	s_add_u32 s69, s86, 0x2601000
	s_addc_u32 s84, s87, 0
	s_cmpk_lt_i32 s58, 0x800
	s_cselect_b64 s[2:3], -1, 0
	v_writelane_b32 v252, s2, 10
	s_lshl_b32 s7, s5, 8
	s_mov_b32 s90, s59
	v_writelane_b32 v252, s3, 11
	s_add_u32 s2, s86, 0x1a601080
	s_addc_u32 s3, s87, 0
	v_writelane_b32 v252, s2, 12
	v_cvt_f32_u32_e32 v1, s59
	v_and_b32_e32 v213, 0x3ff, v0
	v_writelane_b32 v252, s3, 13
	s_add_u32 s2, s86, 0x1a601780
	s_addc_u32 s3, s87, 0
	v_writelane_b32 v252, s2, 14
	s_cmp_lt_u32 s58, 16
	v_rcp_iflag_f32_e32 v1, v1
	v_writelane_b32 v252, s3, 15
	s_cselect_b64 s[2:3], -1, 0
	v_writelane_b32 v252, s2, 16
	v_mul_f32_e32 v1, 0x4f7ffffe, v1
	v_cvt_u32_f32_e32 v1, v1
	v_writelane_b32 v252, s3, 17
	s_lshl_b32 s2, s58, 16
	s_add_u32 s2, s86, s2
	s_addc_u32 s3, s87, 0
	s_add_u32 s2, s2, 0x33601000
	s_addc_u32 s3, s3, 0
	v_writelane_b32 v252, s2, 18
	v_and_b32_e32 v0, 0x3fffffff, v0
	v_mov_b32_e32 v189, 0
	v_writelane_b32 v252, s3, 19
	s_lshl_b32 s2, s58, 11
	s_mov_b32 s12, s2
	s_mov_b32 s3, s91
	v_writelane_b32 v252, s12, 20
	s_lshl_b64 s[2:3], s[2:3], 2
	v_mov_b32_e32 v215, 1
	v_writelane_b32 v252, s13, 21
	s_add_u32 s12, s8, s2
	v_writelane_b32 v252, s8, 22
	s_addc_u32 s13, s9, s3
	s_add_u32 s2, s10, s2
	v_writelane_b32 v252, s9, 23
	v_writelane_b32 v252, s12, 24
	v_mov_b32_e32 v210, 0x3000
	v_mov_b32_e32 v212, 0x358637bd
	v_writelane_b32 v252, s13, 25
	v_writelane_b32 v252, s10, 26
	s_addc_u32 s3, s11, s3
	s_cmp_gt_u32 s59, 16
	v_writelane_b32 v252, s11, 27
	v_writelane_b32 v252, s2, 28
	s_load_dwordx16 s[8:23], s[0:1], 0x40
	v_mov_b64_e32 v[216:217], 0x800
	v_writelane_b32 v252, s3, 29
	s_cselect_b64 s[2:3], -1, 0
	v_writelane_b32 v252, s2, 30
	v_mov_b64_e32 v[250:251], 0x7ff
	v_mov_b64_e32 v[206:207], 0xff
	v_writelane_b32 v252, s3, 31
	s_add_u32 s2, s76, 0x8000000
	v_writelane_b32 v252, s2, 32
	s_addc_u32 s2, s77, 0
	v_writelane_b32 v252, s2, 33
	s_add_u32 s2, s86, 0x16601000
	v_writelane_b32 v252, s2, 34
	s_addc_u32 s2, s87, 0
	v_writelane_b32 v252, s2, 35
	s_add_i32 s2, s59, -16
	s_cmpk_lt_i32 s58, 0x810
	v_writelane_b32 v252, s2, 36
	s_cselect_b64 s[2:3], -1, 0
	v_writelane_b32 v252, s2, 37
	v_mov_b64_e32 v[208:209], 0x100
	v_mov_b32_e32 v214, 0x41b17218
	v_writelane_b32 v252, s3, 38
	s_add_i32 s2, s58, -16
	v_writelane_b32 v252, s2, 39
	s_waitcnt lgkmcnt(0)
	s_add_u32 s85, s20, 0x8000000
	v_writelane_b32 v252, s8, 40
	s_addc_u32 s2, s21, 0
	v_mov_b32_e32 v218, 0x42800000
	v_writelane_b32 v252, s9, 41
	v_writelane_b32 v252, s10, 42
	v_writelane_b32 v252, s11, 43
	v_writelane_b32 v252, s12, 44
	v_writelane_b32 v252, s13, 45
	v_writelane_b32 v252, s14, 46
	v_writelane_b32 v252, s15, 47
	v_writelane_b32 v252, s16, 48
	v_writelane_b32 v252, s17, 49
	v_writelane_b32 v252, s18, 50
	v_writelane_b32 v252, s19, 51
	v_writelane_b32 v252, s20, 52
	v_writelane_b32 v252, s21, 53
	v_writelane_b32 v252, s22, 54
	v_writelane_b32 v252, s23, 55
	v_writelane_b32 v252, s2, 56
	s_add_u32 s2, s86, 0x6601000
	v_writelane_b32 v252, s2, 57
	s_addc_u32 s2, s87, 0
	v_writelane_b32 v252, s2, 58
	s_add_u32 s2, s86, 0x1c601000
	s_addc_u32 s3, s87, 0
	s_add_u32 s12, s86, 0x31601000
	s_addc_u32 s13, s87, 0
	s_add_u32 s34, s86, 0x2201000
	s_addc_u32 s35, s87, 0
	v_writelane_b32 v252, s2, 59
	s_cmpk_lt_i32 s58, 0x100
	v_not_b32_e32 v219, 63
	v_writelane_b32 v252, s3, 60
	s_cselect_b64 s[2:3], -1, 0
	v_writelane_b32 v252, s2, 61
	v_mov_b32_e32 v220, 0xf149f2ca
	v_mov_b32_e32 v221, 0xffffe4e0
	v_writelane_b32 v252, s3, 62
	s_lshl_b32 s2, s5, 5
	s_add_u32 s36, s86, 0x1c01000
	s_addc_u32 s37, s87, 0
	s_add_u32 s8, s86, 0x39861000
	s_addc_u32 s9, s87, 0
	v_writelane_b32 v252, s8, 63
	s_movk_i32 s92, 0x2000
	s_movk_i32 s93, 0x400
	v_writelane_b32 v253, s9, 0
	s_add_u32 s8, s86, 0x34841000
	s_addc_u32 s9, s87, 0
	v_writelane_b32 v253, s8, 1
	s_add_u32 s3, s86, 0x35861000
	s_mov_b32 s60, 0xbfb8aa3b
	v_writelane_b32 v253, s9, 2
	v_writelane_b32 v253, s3, 3
	s_addc_u32 s3, s87, 0
	v_writelane_b32 v253, s3, 4
	s_add_u32 s3, s86, 0x37861000
	v_writelane_b32 v253, s3, 5
	s_addc_u32 s3, s87, 0
	s_add_u32 s8, s86, 0x33841000
	v_writelane_b32 v253, s3, 6
	s_addc_u32 s9, s87, 0
	v_writelane_b32 v253, s8, 7
	s_add_u32 s96, s86, 0x35841000
;     __device__ __forceinline__ bool next(int i0, Unit& u) const {
;         const int i = i0 / nbr; u.br = i0 - i * nbr;
;         const long L = (long)i * G + c; if (L >= nwg) return false;
;         int wgid = (int)L; { const int q = nwg / NXCD, r = nwg % NXCD, xcd = wgid % NXCD, off = wgid / NXCD; wgid = (xcd < r ? xcd * (q + 1) : r * (q + 1) + (xcd - r) * q) + off; }
;         const int nig = WGM * nN, gid = wgid / nig, fm = gid * WGM, gsz = (nM - fm) < WGM ? (nM - fm) : WGM;
;         u.pm = fm + ((wgid % nig) % gsz); u.pn = (wgid % nig) / gsz; return true;
	s_addc_u32 s97, s87, 0
	v_writelane_b32 v253, s9, 8
	s_lshl_b32 s3, s58, 9
	v_writelane_b32 v253, s3, 9
	s_lshl_b32 s3, s59, 9
	s_add_u32 s8, s86, 0x2f601000
	v_writelane_b32 v253, s3, 10
	s_addc_u32 s9, s87, 0
	v_writelane_b32 v253, s8, 11
	s_add_u32 s3, s86, 0x1000
	s_movk_i32 s63, 0x3800
	v_writelane_b32 v253, s9, 12
	v_writelane_b32 v253, s3, 13
	s_addc_u32 s3, s87, 0
	s_cmpk_lt_i32 s58, 0x700
	v_writelane_b32 v253, s3, 14
	s_cselect_b64 s[8:9], -1, 0
	v_writelane_b32 v253, s8, 15
	s_cmp_lt_i32 s5, 0
	s_mul_i32 s3, s5, 0x41
	v_writelane_b32 v253, s9, 16
	s_cselect_b32 s8, s3, s6
	s_mul_i32 s3, s5, 0x101
	s_cselect_b32 s10, s3, s7
	s_movk_i32 s3, 0xe1
	s_cselect_b32 s3, s3, 0xe0
	s_mul_i32 s3, s3, s5
	s_mul_i32 s5, s5, 33
	s_cselect_b32 s11, s5, s2
	s_add_i32 s3, s3, s4
	s_mul_hi_i32 s2, s3, 0x92492493
	s_add_i32 s2, s2, s3
	s_lshr_b32 s5, s2, 31
	s_ashr_i32 s2, s2, 7
	s_add_i32 s2, s2, s5
	s_mul_i32 s5, s2, 0xe0
	s_sub_i32 s3, s3, s5
	s_bfe_u32 s5, s3, 0x3001c
	s_add_i32 s5, s3, s5
	s_and_b32 s6, s5, 0xfff8
	s_sub_i32 s3, s3, s6
	s_lshl_b32 s2, s2, 3
	s_sext_i32_i16 s5, s5
	s_sext_i32_i16 s3, s3
	s_add_i32 s14, s2, s3
	s_ashr_i32 s2, s5, 3
	v_writelane_b32 v253, s2, 17
	s_mov_b32 s6, s14
	s_ashr_i32 s15, s14, 31
	v_writelane_b32 v253, s6, 18
	s_lshr_b32 s2, s5, 3
	s_mov_b32 s70, 0x7f800000
	v_writelane_b32 v253, s7, 19
	s_lshl_b64 s[6:7], s[14:15], 19
	s_add_u32 s6, s66, s6
	s_addc_u32 s7, s67, s7
	s_bfe_i64 s[2:3], s[2:3], 0x100000
	s_lshl_b64 s[2:3], s[2:3], 19
	v_writelane_b32 v253, s2, 20
	s_mov_b32 s74, 0x3f317217
	s_mov_b32 s75, 0x3d800000
	v_writelane_b32 v253, s3, 21
	s_add_u32 s2, s6, 0x40000
	v_writelane_b32 v253, s6, 22
	s_addc_u32 s3, s7, 0
	s_lshl_b32 s14, s58, 2
	v_writelane_b32 v253, s7, 23
	v_writelane_b32 v253, s2, 24
	s_cmpk_lt_i32 s58, 0x368
	s_mov_b32 s71, 0x43000000
	v_writelane_b32 v253, s3, 25
	s_cselect_b64 s[2:3], -1, 0
	v_writelane_b32 v253, s2, 26
	s_add_i32 s5, s59, s58
	s_mov_b32 s65, 0xc2fc0000
	v_writelane_b32 v253, s3, 27
	s_add_u32 s2, s86, 0x1d01000
	v_writelane_b32 v253, s2, 28
	s_addc_u32 s2, s87, 0
	v_writelane_b32 v253, s2, 29
	s_add_u32 s2, s86, 0x1e01000
	v_writelane_b32 v253, s2, 30
	s_addc_u32 s2, s87, 0
	v_writelane_b32 v253, s2, 31
	s_add_u32 s2, s86, 0xa601000
	v_writelane_b32 v253, s2, 32
	s_addc_u32 s2, s87, 0
	s_cmpk_lt_i32 s58, 0x1000
	v_writelane_b32 v253, s2, 33
	s_cselect_b64 s[2:3], -1, 0
	v_writelane_b32 v253, s2, 34
	s_mov_b64 s[88:89], 0x100
	s_mov_b64 s[38:39], 0x40100
	v_writelane_b32 v253, s3, 35
	s_add_i32 s2, s8, s4
	s_ashr_i32 s3, s2, 31
	s_lshr_b32 s3, s3, 27
	s_add_i32 s6, s2, s3
	s_and_b32 s3, s6, 0xffe0
	s_sub_i32 s2, s2, s3
	s_bfe_i32 s3, s2, 0x80000
	s_bfe_u32 s3, s3, 0x3000c
	s_add_i32 s7, s2, s3
	s_and_b32 s3, s7, 0xf8
	s_sub_i32 s8, s2, s3
	s_ashr_i32 s6, s6, 5
	s_bfe_i32 s7, s7, 0x80000
	s_lshl_b32 s6, s6, 3
	s_sext_i32_i16 s7, s7
	s_sext_i32_i8 s8, s8
	s_add_i32 s16, s6, s8
	s_ashr_i32 s6, s7, 3
	v_writelane_b32 v253, s6, 36
	s_lshl_b64 s[8:9], s[90:91], 9
	s_mov_b32 s2, s58
	s_mov_b32 s3, s91
	v_writelane_b32 v253, s8, 37
	s_ashr_i32 s17, s16, 31
	s_lshr_b32 s6, s7, 3
	v_writelane_b32 v253, s9, 38
	s_lshl_b64 s[8:9], s[2:3], 9
	v_writelane_b32 v253, s8, 39
	s_nop 1
	v_writelane_b32 v253, s9, 40
	s_lshl_b64 s[8:9], s[90:91], 11
	v_writelane_b32 v253, s8, 41
	s_nop 1
	v_writelane_b32 v253, s9, 42
	s_lshl_b64 s[8:9], s[16:17], 20
	s_add_u32 s18, s94, s8
	s_mov_b32 s8, s16
	s_addc_u32 s19, s95, s9
	v_writelane_b32 v253, s8, 43
	s_bfe_i64 s[6:7], s[6:7], 0x100000
	s_lshl_b64 s[6:7], s[6:7], 20
	v_writelane_b32 v253, s9, 44
	s_ashr_i32 s8, s16, 3
	s_ashr_i32 s9, s8, 31
	s_lshl_b64 s[8:9], s[8:9], 22
	v_writelane_b32 v253, s8, 45
	s_nop 1
	v_writelane_b32 v253, s9, 46
	v_writelane_b32 v253, s6, 47
	s_nop 1
	v_writelane_b32 v253, s7, 48
	s_add_u32 s6, s18, 0x80000
	v_writelane_b32 v253, s18, 49
	s_addc_u32 s7, s19, 0
	s_nop 0
	v_writelane_b32 v253, s19, 50
	v_writelane_b32 v253, s6, 51
	s_nop 1
	v_writelane_b32 v253, s7, 52
	s_add_i32 s6, s10, s4
	s_ashr_i32 s7, s6, 31
	s_lshr_b32 s7, s7, 25
	s_add_i32 s7, s6, s7
	s_and_b32 s8, s7, 0xff80
	s_sub_i32 s6, s6, s8
	s_bfe_i32 s8, s6, 0x80000
	s_bfe_u32 s8, s8, 0x3000c
	s_add_i32 s8, s6, s8
	s_and_b32 s9, s8, 0xf8
	s_sub_i32 s6, s6, s9
	s_ashr_i32 s7, s7, 7
	s_lshl_b32 s7, s7, 3
	s_sext_i32_i8 s6, s6
	s_add_i32 s4, s11, s4
	s_add_i32 s15, s7, s6
	s_ashr_i32 s6, s4, 31
	s_lshr_b32 s6, s6, 27
	s_add_i32 s9, s4, s6
	s_and_b32 s6, s9, 0xffe0
	s_sub_i32 s4, s4, s6
	s_bfe_i32 s6, s4, 0x80000
	s_bfe_u32 s6, s6, 0x3000c
	s_add_i32 s10, s4, s6
	s_and_b32 s6, s10, 0xf8
	s_sub_i32 s11, s4, s6
	s_ashr_i32 s6, s15, 3
	s_ashr_i32 s7, s6, 31
	s_bfe_i32 s4, s8, 0x80000
	s_lshl_b64 s[6:7], s[6:7], 22
	s_sext_i32_i16 s4, s4
	v_writelane_b32 v253, s6, 53
	s_nop 1
	v_writelane_b32 v253, s7, 54
	s_ashr_i32 s6, s4, 3
	s_lshr_b32 s4, s4, 3
	v_writelane_b32 v253, s6, 55
	s_bfe_i64 s[6:7], s[4:5], 0x100000
	s_lshl_b64 s[6:7], s[6:7], 18
	v_writelane_b32 v253, s6, 56
	s_ashr_i32 s4, s9, 5
	s_lshl_b32 s4, s4, 3
	v_writelane_b32 v253, s7, 57
	s_bfe_i32 s6, s10, 0x80000
	s_sext_i32_i8 s7, s11
	s_sext_i32_i16 s6, s6
	s_add_i32 s8, s4, s7
	v_writelane_b32 v253, s15, 58
	s_lshl_b32 s4, s15, 8
	s_ashr_i32 s9, s8, 31
	v_writelane_b32 v253, s4, 59
	s_ashr_i32 s4, s6, 3
	v_writelane_b32 v253, s4, 60
	s_lshr_b32 s4, s6, 3
	s_lshl_b64 s[6:7], s[8:9], 19
	s_add_u32 s10, s12, s6
	v_writelane_b32 v253, s12, 61
	s_addc_u32 s11, s13, s7
	s_bfe_i64 s[6:7], s[4:5], 0x100000
	v_writelane_b32 v253, s13, 62
	s_lshl_b64 s[12:13], s[6:7], 19
	v_writelane_b32 v253, s12, 63
	s_mov_b32 s4, s8
	s_nop 0
	v_writelane_b32 v254, s13, 0
	s_add_u32 s12, s10, 0x40000
; __device__ void phase_convert(const Params& p, LAS unsigned char* lds) {
;     ...
;     cvt_job(tile, p.w_in, (bf16_t*)(ws + WS_WIN), NL, 1024, NIN, 1024, 0, (size_t)1024 * NIN, (size_t)NP * 1024, (int)blockIdx.x, (int)gridDim.x, 3072);
;     cvt_job(tile, p.wba, (bf16_t*)(ws + WS_WMRG), NL, 512, 1024, 512, 0, (size_t)512 * 1024, (size_t)3 * 1024 * 512, (int)((blockIdx.x + gridDim.x - 104 % gridDim.x) % gridDim.x), (int)gridDim.x);
;     cvt_job(tile, p.wbc, (bf16_t*)(ws + WS_WMRG) + (size_t)1024 * 512, NL, 512, 1024, 512, 0, (size_t)512 * 1024, (size_t)3 * 1024 * 512, (int)((blockIdx.x + gridDim.x - 168 % gridDim.x) % gridDim.x), (int)gridDim.x);
;     cvt_job(tile, p.wbg, (bf16_t*)(ws + WS_WMRG) + (size_t)2 * 1024 * 512, NL, 512, 1024, 512, 0, (size_t)512 * 1024, (size_t)3 * 1024 * 512, (int)((blockIdx.x + gridDim.x - 232 % gridDim.x) % gridDim.x), (int)gridDim.x);
;     cvt_job(tile, p.w_out, (bf16_t*)(ws + WS_WOUT), NL, 1024, 1024, 1024, 0, (size_t)1024 * 1024, (size_t)1024 * 1024, (int)((blockIdx.x + gridDim.x - 40 % gridDim.x) % gridDim.x), (int)gridDim.x);
	v_writelane_b32 v254, s10, 1
	s_addc_u32 s13, s11, 0
	s_lshl_b64 s[8:9], s[8:9], 18
	v_writelane_b32 v254, s11, 2
	v_writelane_b32 v254, s12, 3
	s_add_u32 s8, s24, s8
	s_nop 0
	v_writelane_b32 v254, s13, 4
	v_writelane_b32 v254, s4, 5
	s_nop 1
	v_writelane_b32 v254, s5, 6
	v_writelane_b32 v254, s24, 7
	s_addc_u32 s9, s25, s9
	s_lshl_b64 s[6:7], s[6:7], 18
	v_writelane_b32 v254, s25, 8
	v_writelane_b32 v254, s6, 9
	s_nop 1
	v_writelane_b32 v254, s7, 10
	s_add_u32 s6, s8, 0x20000
	v_writelane_b32 v254, s8, 11
	s_addc_u32 s7, s9, 0
	s_nop 0
	v_writelane_b32 v254, s9, 12
	v_writelane_b32 v254, s6, 13
	s_nop 1
	v_writelane_b32 v254, s7, 14
	v_sub_co_u32_e64 v2, s[6:7], 0, s59
	s_nop 0
	v_readfirstlane_b32 s4, v2
	v_writelane_b32 v254, s6, 15
	s_nop 1
	v_writelane_b32 v254, s7, 16
	v_readfirstlane_b32 s6, v1
	s_mul_i32 s4, s4, s6
	s_mul_hi_u32 s4, s6, s4
	s_add_i32 s6, s6, s4
	s_mul_hi_u32 s4, s6, 0x68
	s_mul_i32 s4, s4, s59
	s_sub_i32 s4, 0x68, s4
	s_sub_i32 s7, s4, s59
	s_cmp_ge_u32 s4, s59
	s_cselect_b32 s4, s7, s4
	s_sub_i32 s7, s4, s59
	s_cmp_ge_u32 s4, s59
	s_cselect_b32 s4, s7, s4
	s_sub_i32 s4, s5, s4
	s_mul_hi_u32 s7, s4, s6
	s_mul_i32 s7, s7, s59
	s_sub_i32 s4, s4, s7
	s_sub_i32 s7, s4, s59
	s_cmp_ge_u32 s4, s59
	s_cselect_b32 s4, s7, s4
	s_sub_i32 s7, s4, s59
	s_cmp_ge_u32 s4, s59
	s_cselect_b32 s8, s7, s4
	s_mul_hi_u32 s4, s6, 0xa8
	s_cmp_lt_i32 s8, 64
	s_mul_i32 s4, s4, s59
	s_cselect_b64 s[10:11], -1, 0
	s_sub_i32 s4, 0xa8, s4
	s_sub_i32 s7, s4, s59
	s_cmp_ge_u32 s4, s59
	s_cselect_b32 s4, s7, s4
	s_sub_i32 s7, s4, s59
	s_cmp_ge_u32 s4, s59
	s_cselect_b32 s4, s7, s4
	s_sub_i32 s4, s5, s4
	s_mul_hi_u32 s7, s4, s6
	s_mul_i32 s7, s7, s59
	s_sub_i32 s4, s4, s7
	s_sub_i32 s7, s4, s59
	s_cmp_ge_u32 s4, s59
	s_cselect_b32 s4, s7, s4
	s_sub_i32 s7, s4, s59
	s_cmp_ge_u32 s4, s59
	s_cselect_b32 s9, s7, s4
	s_mul_hi_u32 s4, s6, 0xe8
	v_writelane_b32 v254, s10, 17
	s_cmp_lt_i32 s9, 64
	s_mul_i32 s4, s4, s59
	v_writelane_b32 v254, s11, 18
	s_cselect_b64 s[10:11], -1, 0
	s_sub_i32 s4, 0xe8, s4
	s_sub_i32 s7, s4, s59
	s_cmp_ge_u32 s4, s59
	s_cselect_b32 s4, s7, s4
	s_sub_i32 s7, s4, s59
	s_cmp_ge_u32 s4, s59
	s_cselect_b32 s4, s7, s4
	s_sub_i32 s4, s5, s4
	s_mul_hi_u32 s7, s4, s6
	s_mul_i32 s7, s7, s59
	s_sub_i32 s4, s4, s7
	s_sub_i32 s7, s4, s59
	s_cmp_ge_u32 s4, s59
	s_cselect_b32 s4, s7, s4
	s_sub_i32 s7, s4, s59
	v_writelane_b32 v254, s10, 19
	s_cmp_ge_u32 s4, s59
	v_mbcnt_lo_u32_b32 v1, -1, 0
	v_writelane_b32 v254, s11, 20
	s_cselect_b32 s10, s7, s4
	s_mul_hi_u32 s4, s6, 40
	s_cmp_lt_i32 s10, 64
	s_mul_i32 s4, s4, s59
	s_cselect_b64 s[12:13], -1, 0
	s_sub_i32 s4, 40, s4
	s_sub_i32 s7, s4, s59
	s_cmp_ge_u32 s4, s59
	s_cselect_b32 s4, s7, s4
	s_sub_i32 s7, s4, s59
	s_cmp_ge_u32 s4, s59
	s_cselect_b32 s4, s7, s4
	s_sub_i32 s4, s5, s4
	s_mul_hi_u32 s5, s4, s6
	s_mul_i32 s5, s5, s59
	s_sub_i32 s4, s4, s5
	s_sub_i32 s5, s4, s59
	s_cmp_ge_u32 s4, s59
	s_cselect_b32 s4, s5, s4
	s_sub_i32 s5, s4, s59
	s_cmp_ge_u32 s4, s59
	s_cselect_b32 s4, s5, s4
	v_writelane_b32 v254, s12, 21
	s_cmpk_lt_i32 s4, 0x80
	s_cselect_b64 s[6:7], -1, 0
	v_writelane_b32 v254, s13, 22
	v_writelane_b32 v254, s6, 23
	v_mbcnt_hi_u32_b32 v211, -1, v1
	s_nop 0
	v_writelane_b32 v254, s7, 24
	s_lshl_b64 s[6:7], s[90:91], 13
	v_writelane_b32 v254, s6, 25
	s_nop 1
	v_writelane_b32 v254, s7, 26
	s_lshl_b64 s[6:7], s[90:91], 12
	v_writelane_b32 v254, s6, 27
	s_nop 1
	v_writelane_b32 v254, s7, 28
	s_add_u32 s6, s86, 0x800
	s_addc_u32 s7, s87, 0
	v_writelane_b32 v254, s6, 29
	s_sub_i32 s5, s14, 64
	s_ashr_i32 s31, s30, 31
	v_writelane_b32 v254, s7, 30
	v_writelane_b32 v254, s14, 31
	v_writelane_b32 v254, s5, 32
	s_lshl_b32 s5, s59, 2
	v_writelane_b32 v254, s5, 33
	s_sub_i32 s5, s5, 64
	v_writelane_b32 v254, s5, 34
	s_lshl_b32 s5, s59, 11
	v_writelane_b32 v254, s5, 35
	v_writelane_b32 v254, s8, 36
	s_lshl_b32 s5, s8, 2
	v_writelane_b32 v254, s5, 37
	v_writelane_b32 v254, s9, 38
	s_lshl_b32 s5, s9, 2
	v_writelane_b32 v254, s5, 39
	v_writelane_b32 v254, s10, 40
	s_lshl_b32 s5, s10, 2
	v_writelane_b32 v254, s5, 41
	v_writelane_b32 v254, s4, 42
	s_lshl_b32 s4, s4, 2
	v_writelane_b32 v254, s4, 43
	s_lshl_b64 s[4:5], s[30:31], 2
	s_load_dwordx16 s[8:23], s[0:1], 0x0
	v_writelane_b32 v254, s4, 44
	s_nop 1
	v_writelane_b32 v254, s5, 45
	s_lshl_b64 s[4:5], s[30:31], 11
	v_writelane_b32 v254, s4, 46
	s_nop 1
	v_writelane_b32 v254, s5, 47
	s_lshl_b64 s[4:5], s[2:3], 13
	s_waitcnt lgkmcnt(0)
	s_add_u32 s0, s8, s4
	v_writelane_b32 v254, s8, 48
	s_addc_u32 s1, s9, s5
	v_writelane_b32 v255, s0, 0
	v_writelane_b32 v254, s9, 49
	v_writelane_b32 v254, s10, 50
	v_writelane_b32 v255, s1, 1
	s_lshl_b64 s[0:1], s[2:3], 12
	s_lshl_b64 s[2:3], s[90:91], 15
	v_writelane_b32 v255, s2, 2
	v_writelane_b32 v254, s11, 51
	s_mov_b32 s4, s30
	v_writelane_b32 v255, s3, 3
	s_lshl_b64 s[2:3], s[90:91], 14
	s_add_u32 s0, s86, s0
	s_addc_u32 s1, s87, s1
	v_writelane_b32 v255, s2, 4
	s_add_u32 s0, s0, 0x1a601000
	s_addc_u32 s1, s1, 0
	v_writelane_b32 v255, s3, 5
	v_writelane_b32 v255, s0, 6
	s_add_i32 s2, 0, 0x10400
	v_writelane_b32 v254, s12, 52
	v_writelane_b32 v255, s1, 7
	s_mul_hi_u32 s1, s59, 0x600
	s_mul_i32 s0, s59, 0x600
	v_writelane_b32 v255, s0, 8
	v_writelane_b32 v254, s13, 53
	v_writelane_b32 v254, s14, 54
	v_writelane_b32 v255, s1, 9
	s_mul_hi_u32 s1, s59, 0x6000
	s_mul_i32 s0, s59, 0x6000
	v_writelane_b32 v255, s0, 10
	v_writelane_b32 v254, s15, 55
	v_writelane_b32 v254, s16, 56
	v_writelane_b32 v255, s1, 11
	s_mul_hi_u32 s1, s59, 0x3000
	s_mul_i32 s0, s59, 0x3000
	v_writelane_b32 v255, s0, 12
	v_writelane_b32 v254, s17, 57
	v_writelane_b32 v254, s18, 58
	v_writelane_b32 v255, s1, 13
	v_writelane_b32 v255, s2, 14
	s_add_i32 s2, 0, 0x1040c
	v_writelane_b32 v255, s2, 15
	s_add_i32 s2, 0, 0x10408
	v_writelane_b32 v255, s2, 16
	v_cmp_eq_u32_e64 s[2:3], 0, v213
	v_writelane_b32 v254, s19, 59
	v_writelane_b32 v254, s20, 60
	v_writelane_b32 v255, s2, 17
	v_writelane_b32 v254, s21, 61
	v_writelane_b32 v254, s22, 62
	v_writelane_b32 v255, s3, 18
	v_cmp_eq_u32_e64 s[2:3], 0, v0
	v_writelane_b32 v254, s23, 63
	s_mov_b32 s0, 0xffff0000
	v_writelane_b32 v255, s2, 19
	s_mov_b32 s1, 0x800000
	s_mov_b32 s16, s56
	v_writelane_b32 v255, s3, 20
	v_writelane_b32 v255, s66, 21
	s_mov_b64 s[2:3], 0x180
	s_nop 0
	v_writelane_b32 v255, s67, 22
	v_writelane_b32 v255, s28, 23
	s_nop 1
	v_writelane_b32 v255, s29, 24
	v_writelane_b32 v255, s4, 25
	s_nop 1
	v_writelane_b32 v255, s5, 26
	v_writelane_b32 v255, s33, 27
	v_writelane_b32 v255, s68, 28
	v_writelane_b32 v255, s69, 29
	v_writelane_b32 v255, s84, 30
	v_writelane_b32 v255, s34, 31
	v_writelane_b32 v255, s35, 32
	v_writelane_b32 v255, s36, 33
	v_writelane_b32 v255, s37, 34
	v_writelane_b32 v255, s72, 35
	s_nop 1
	v_writelane_b32 v255, s73, 36
	v_writelane_b32 v255, 0, 62
	v_writelane_b32 v255, 0, 63
	s_branch .LBB0_4

; __device__ __forceinline__ int fresh_tid() { int t = threadIdx.x; asm volatile("" : "+v"(t)); return t; }
; #define PG8_STAGE_A(bufoff, gbase, h) do { if constexpr (GATHER) PG8_STAGE(bufoff, gbase, go[h][0], go[h][1]); else PG8_STAGE(bufoff, (gbase) + (h) * hstep, voffA[0], voffA[1]); } while (0)
; #define PG8_BAR __builtin_amdgcn_s_barrier()
; #define PG8_GOFFS(u) do { _Pragma("unroll") for (int h = 0; h < 2; ++h) _Pragma("unroll") for (int i = 0; i < 2; ++i) \
;         go[h][i] = (unsigned)(S.idx[(u).pm * BM + h * HALF + R0 + 64 * i] * K + C0) * 2u; } while (0)
; template <bool GATHER, class Epi>
; __device__ __forceinline__ void gemm_phase(LAS unsigned char* lds, const Sched& S, const Epi& E) {
;     const int tid = fresh_tid(), wid = __builtin_amdgcn_readfirstlane(tid >> 6), lane = tid & 63, wr = wid >> 2, wc = wid & 3, fr = lane & 15, fq = lane >> 4;
;     const int K = S.K, nt = K / BK;
;     int R0, C0; unsigned voffA[2], voffB[2];
;     { int R, C; stage_rc(tid * 16, R, C); R0 = R; C0 = C; }
; #pragma unroll
;     for (int i = 0; i < 2; ++i) { int R, C; stage_rc(tid * 16 + i * 8192, R, C); const int Rb = Epi::PERM ? ((R & ~31) + perm32(R & 31)) : R; voffA[i] = (unsigned)(R * K + C) * 2u; voffB[i] = (unsigned)(Rb * K + C) * 2u; }
;     ...
;     const char* cA = GATHER ? S.A : S.A + (size_t)cur.pm * tstep + (size_t)cur.br * S.abr; const char* cB = S.bptr(cur);
;     if constexpr (GATHER) PG8_GOFFS(cur);
;     PG8_STAGE(PG8_SB(0, 0), cB, voffB[0], voffB[1]); PG8_STAGE_A(PG8_SA(0, 0), cA, 0); PG8_STAGE(PG8_SB(0, 1), cB + b1off, voffB[0], voffB[1]); PG8_STAGE_A(PG8_SA(0, 1), cA, 1);
;     if (wr == 1) PG8_BAR;
.LBB0_493:
	s_and_b64 vcc, exec, s[4:5]
	s_cbranch_vccz .LBB0_511
	v_readlane_b32 s4, v255, 38
	s_cmp_lg_u32 s4, 0
	s_cbranch_scc1 .LBB0_511
	v_readlane_b32 s6, v255, 37
	s_cmp_lg_u32 s6, 1
	s_cbranch_scc1 .Lp1_proj
	v_readlane_b32 s6, v255, 62
	s_cmp_lg_u32 s6, 0
	s_cbranch_scc1 .Lp1_proj
	s_bitcmp1_b32 s58, 3
	s_cbranch_scc1 .Lp1_x
	v_writelane_b32 v255, 2, 62
	s_branch .Lp1_proj
.Lp1_x:
	v_writelane_b32 v255, 1, 62
	s_branch .LBB0_543
.Lp1_proj:
	v_readlane_b32 s4, v253, 15
	s_waitcnt vmcnt(0)
	v_mov_b32_e32 v0, v213
	v_readlane_b32 s5, v253, 16
	s_andn2_b64 vcc, exec, s[4:5]
	v_readfirstlane_b32 s20, v0
	s_cbranch_vccnz .LBB0_511
	v_bfe_i32 v3, v0, 27, 1
	v_lshlrev_b32_e32 v1, 4, v0
	v_lshrrev_b32_e32 v3, 22, v3
	v_add_u32_e32 v3, v1, v3
	v_and_b32_e32 v3, 0xfffffc00, v3
	v_sub_u32_e32 v3, v1, v3
	v_ashrrev_i32_e32 v2, 31, v0
	v_lshrrev_b32_e32 v4, 4, v3
	v_lshrrev_b32_e32 v2, 26, v2
	v_bitop3_b32 v4, v4, v3, 32 bitop3:0x6c
	v_ashrrev_i32_e32 v3, 31, v3
	v_add_u32_e32 v2, v0, v2
	v_lshrrev_b32_e32 v3, 26, v3
	v_ashrrev_i32_e32 v2, 6, v2
	v_add_u32_e32 v3, v4, v3
	v_lshlrev_b32_e32 v5, 3, v2
	v_ashrrev_i32_e32 v3, 6, v3
	s_mul_i32 s5, s26, 0xe00000
	v_readlane_b32 s6, v253, 13
	v_and_b32_e32 v5, -16, v5
	v_mul_i32_i24_e32 v6, 64, v3
	s_mul_hi_i32 s4, s26, 0xe00000
	s_add_u32 s21, s6, s5
	v_readlane_b32 s5, v253, 14
	v_add_u32_e32 v5, v3, v5
	v_sub_u32_e32 v4, v4, v6
	s_addc_u32 s22, s5, s4
	v_lshlrev_b32_e32 v2, 5, v2
	v_ashrrev_i16_sdwa v4, v215, sext(v4) dst_sel:DWORD dst_unused:UNUSED_PAD src0_sel:DWORD src1_sel:BYTE_0
	v_lshlrev_b32_e32 v6, 1, v5
	v_lshrrev_b32_e32 v7, 2, v5
	v_and_b32_e32 v3, 3, v3
	s_mov_b32 s4, 0x1fffe0
	v_and_b32_e32 v2, 32, v2
	v_bfe_i32 v4, v4, 0, 16
	v_and_b32_e32 v6, 24, v6
	v_and_b32_e32 v7, 4, v7
	v_and_or_b32 v3, v5, s4, v3
	v_or3_b32 v3, v3, v7, v6
	v_add_lshl_u32 v2, v2, v4, 1
	v_add_u32_e32 v1, 0x2000, v1
	v_lshl_add_u32 v132, v5, 11, v2
	v_lshl_add_u32 v133, v3, 11, v2
	v_ashrrev_i32_e32 v2, 31, v1
	v_lshrrev_b32_e32 v2, 22, v2
	v_add_u32_e32 v2, v1, v2
	v_ashrrev_i32_e32 v2, 10, v2
	v_mul_i32_i24_e32 v3, 0x400, v2
	v_sub_u32_e32 v1, v1, v3
	v_lshrrev_b32_e32 v3, 4, v1
	v_bitop3_b32 v1, v3, v1, 32 bitop3:0x6c
	v_ashrrev_i32_e32 v4, 31, v1
	v_lshrrev_b32_e32 v4, 26, v4
	v_lshlrev_b32_e32 v3, 3, v2
	v_add_u32_e32 v4, v1, v4
	v_and_b32_e32 v3, -16, v3
	v_ashrrev_i32_e32 v5, 6, v4
	v_and_b32_e32 v4, 0xc0, v4
	v_add_u32_e32 v3, v5, v3
	v_sub_u32_e32 v1, v1, v4
	s_ashr_i32 s5, s20, 6
	v_lshlrev_b32_e32 v2, 5, v2
	v_ashrrev_i16_sdwa v1, v215, sext(v1) dst_sel:DWORD dst_unused:UNUSED_PAD src0_sel:DWORD src1_sel:BYTE_0
	v_lshlrev_b32_e32 v4, 1, v3
	v_lshrrev_b32_e32 v6, 2, v3
	v_and_b32_e32 v5, 3, v5
	v_and_b32_e32 v2, 32, v2
	v_bfe_i32 v1, v1, 0, 16
	v_and_b32_e32 v4, 24, v4
	v_and_b32_e32 v6, 4, v6
	v_and_or_b32 v5, v3, s4, v5
	s_ashr_i32 s4, s20, 8
	s_lshl_b32 s23, s5, 10
	v_readlane_b32 s6, v253, 20
	v_or3_b32 v4, v5, v6, v4
	v_add_lshl_u32 v1, v2, v1, 1
	v_readlane_b32 s7, v253, 21
	s_add_u32 s14, s21, s6
	v_lshl_add_u32 v135, v4, 11, v1
	s_addc_u32 s15, s22, s7
	s_add_i32 s24, s23, 0
	v_lshl_add_u32 v134, v3, 11, v1
	v_mov_b32_e32 v1, v133
	v_mov_b32_e32 v2, v135
	s_add_i32 m0, s24, 0x10000
	v_readlane_b32 s6, v253, 22
	global_load_lds_dwordx4 v1, s[14:15]
	s_add_i32 m0, s24, 0x12000
	v_mov_b32_e32 v1, v132
	global_load_lds_dwordx4 v2, s[14:15]
	v_mov_b32_e32 v2, v134
	s_mov_b32 m0, s24
	v_readlane_b32 s7, v253, 23
	s_add_i32 s25, s24, 0x2000
	s_nop 3
	global_load_lds_dwordx4 v1, s[6:7]
	s_mov_b32 m0, s25
	v_mov_b32_e32 v1, v133
	global_load_lds_dwordx4 v2, s[6:7]
	s_add_u32 s6, s14, 0x40000
	v_mov_b32_e32 v2, v135
	s_addc_u32 s7, s15, 0
	s_add_i32 m0, s24, 0x14000
	s_add_i32 s26, s24, 0x4000
	global_load_lds_dwordx4 v1, s[6:7]
	s_add_i32 m0, s24, 0x16000
	v_mov_b32_e32 v1, v132
	global_load_lds_dwordx4 v2, s[6:7]
	v_readlane_b32 s6, v253, 24
	v_mov_b32_e32 v2, v134
	s_mov_b32 m0, s26
	v_readlane_b32 s7, v253, 25
	s_add_i32 s27, s24, 0x6000
	s_cmp_lg_u32 s4, 1
	s_nop 2
	global_load_lds_dwordx4 v1, s[6:7]
	s_mov_b32 m0, s27
	s_nop 0
	global_load_lds_dwordx4 v2, s[6:7]
	s_cbranch_scc1 .LBB0_498
	s_barrier

; __device__ __forceinline__ void run_phase(const Params& p, int ph, LAS unsigned char* lds) {
;     ...
;     if (ph == 0) { phase_convert(p, lds); return; }
;     const int l = (ph - 1) / PH_PER_LAYER, k = (ph - 1) % PH_PER_LAYER;
;     bf16_t* PROJ = (bf16_t*)(ws + WS_PROJ); bf16_t* YCAT = (bf16_t*)(ws + WS_YCAT);
;     switch (k) {
;     case 0: {
;         Sched S; S.A = (const char*)(ws + WS_XB); S.idx = nullptr; S.B0 = (const char*)(ws + WS_WIN) + (size_t)l * NP * 1024 * 2; S.b1off = (size_t)HALF * 1024 * 2; S.bstrideE = 0; S.bRowsPerPn = 256; S.K = 1024; S.init(SEQ / BM, NP / BM);
;         EpiProj E{PROJ, (u32x4*)(ws + WS_GT)}; gemm_phase<false>(lds, S, E); } break;
.LBB0_511:
	v_readlane_b32 s6, v255, 62
	s_cmp_eq_u32 s6, 2
	s_cbranch_scc1 .Lp1_yjobs
	s_cmp_eq_u32 s6, 3
	s_cbranch_scc0 .Lp1_end
	v_writelane_b32 v255, 0, 62

; __device__ __forceinline__ void run_phase(const Params& p, int ph, LAS unsigned char* lds) {
;     ...
;     if (ph == 0) { phase_convert(p, lds); return; }
;     const int l = (ph - 1) / PH_PER_LAYER, k = (ph - 1) % PH_PER_LAYER;
;     bf16_t* PROJ = (bf16_t*)(ws + WS_PROJ); bf16_t* YCAT = (bf16_t*)(ws + WS_YCAT);
;     switch (k) {
;     case 0: {
;         Sched S; S.A = (const char*)(ws + WS_XB); S.idx = nullptr; S.B0 = (const char*)(ws + WS_WIN) + (size_t)l * NP * 1024 * 2; S.b1off = (size_t)HALF * 1024 * 2; S.bstrideE = 0; S.bRowsPerPn = 256; S.K = 1024; S.init(SEQ / BM, NP / BM);
;         EpiProj E{PROJ, (u32x4*)(ws + WS_GT)}; gemm_phase<false>(lds, S, E); } break;
.Lp1_yjobs:
	v_writelane_b32 v255, 4, 62
	s_branch .LBB0_543

; #define LAS __attribute__((address_space(3)))
; __device__ __forceinline__ int fresh_tid() { int t = threadIdx.x; asm volatile("" : "+v"(t)); return t; }
;     const int tid = fresh_tid();
;     const int tk = K / 64, tn = (N + 63) / 64, per = tk * tn, total = batch * per;
;     for (int gi = bid; gi * 4 < total; gi += nb) {
;         f32x4 v[4][2];
; #pragma unroll
;         for (int q = 0; q < 4; ++q) { const int it = gi * 4 + q;
;             v[q][0] = (f32x4){0.f, 0.f, 0.f, 0.f}; v[q][1] = (f32x4){0.f, 0.f, 0.f, 0.f};
;             if (it < total) { const int b = it / per, r = it % per, k0 = (r / tn) * 64, n0 = (r % tn) * 64;
;                 const float* sp = src + (size_t)b * sbs + (size_t)k0 * N + n0; const int c4 = (tid & 15) * 4;
;                 if (n0 + c4 < N) { v[q][0] = *(const f32x4*)(sp + (size_t)(tid >> 4) * N + c4); v[q][1] = *(const f32x4*)(sp + (size_t)((tid >> 4) + 32) * N + c4); } } }
; #pragma unroll
;         for (int q = 0; q < 4; ++q)
; #pragma unroll
;             for (int j = 0; j < 2; ++j) { const int row = (tid >> 4) + 32 * j, c4 = (tid & 15) * 4; LAS float* tp = tile + q * (64 * 65) + row * 65 + c4;
;                 tp[0] = v[q][j][0]; tp[1] = v[q][j][1]; tp[2] = v[q][j][2]; tp[3] = v[q][j][3]; }
; __device__ void phase_convert(const Params& p, LAS unsigned char* lds) {
;     ...
;     cvt_job(tile, p.wba, (bf16_t*)(ws + WS_WMRG), NL, 512, 1024, 512, 0, (size_t)512 * 1024, (size_t)3 * 1024 * 512, (int)((blockIdx.x + gridDim.x - 104 % gridDim.x) % gridDim.x), (int)gridDim.x);
.LBB0_543:
	v_readlane_b32 s6, v255, 62
	s_cmp_eq_u32 s6, 0
	s_cbranch_scc1 .LBB0_760
	v_readlane_b32 s4, v254, 17
	v_readlane_b32 s5, v254, 18
	v_mov_b32_e32 v0, v213
	s_andn2_b64 vcc, exec, s[4:5]
	s_cbranch_vccnz .LBB0_574
	v_ashrrev_i32_e32 v2, 4, v0
	v_ashrrev_i32_e32 v3, 31, v2
	v_lshlrev_b32_e32 v1, 2, v0
	v_lshlrev_b64 v[34:35], 10, v[2:3]
	s_mov_b64 s[4:5], 0x8000
	v_and_b32_e32 v32, 60, v1
	v_lshl_add_u64 v[36:37], v[34:35], 0, s[4:5]
	v_ashrrev_i32_e32 v33, 3, v0
	v_lshlrev_b32_e32 v0, 3, v0
	s_movk_i32 s4, 0x104
	v_lshl_add_u32 v1, v32, 2, 0
	v_and_b32_e32 v38, 56, v0
	v_mul_lo_u32 v0, v2, s4
	v_lshl_add_u32 v39, v33, 2, 0
	v_mul_u32_u24_e32 v40, 0x104, v38
	v_add_u32_e32 v41, v1, v0
	v_readlane_b32 s16, v254, 37
	v_readlane_b32 s17, v254, 36
	s_branch .LBB0_547

; __device__ __forceinline__ void run_phase(const Params& p, int ph, LAS unsigned char* lds) {
;     ...
;     if (ph == 0) { phase_convert(p, lds); return; }
;     const int l = (ph - 1) / PH_PER_LAYER, k = (ph - 1) % PH_PER_LAYER;
;     bf16_t* PROJ = (bf16_t*)(ws + WS_PROJ); bf16_t* YCAT = (bf16_t*)(ws + WS_YCAT);
;     switch (k) {
;     case 0: {
;         Sched S; S.A = (const char*)(ws + WS_XB); S.idx = nullptr; S.B0 = (const char*)(ws + WS_WIN) + (size_t)l * NP * 1024 * 2; S.b1off = (size_t)HALF * 1024 * 2; S.bstrideE = 0; S.bRowsPerPn = 256; S.K = 1024; S.init(SEQ / BM, NP / BM);
;         EpiProj E{PROJ, (u32x4*)(ws + WS_GT)}; gemm_phase<false>(lds, S, E); } break;
.LBB0_760:
	v_readlane_b32 s6, v255, 62
	s_cmp_eq_u32 s6, 1
	s_cbranch_scc0 .Lp1_h3b
	v_writelane_b32 v255, 3, 62
	s_mov_b32 s26, 0
	s_branch .Lp1_proj
.Lp1_h3b:
	s_cmp_eq_u32 s6, 4
	s_cbranch_scc0 .Lp1_h3c
	v_writelane_b32 v255, 0, 62
	s_branch .LBB0_511
